# grid barrier: acquire invalidate issued on arrival (non-leaders) or with the cross-XCC arrival (leader) so it overlaps the wait for the release instead of following it
# speedup vs baseline: 1.0222x; 1.0076x over previous
.LBB0_1506:
	s_or_b64 exec, exec, s[12:13]
	s_waitcnt vmcnt(0)
	v_readfirstlane_b32 s2, v3
	v_sub_u32_e32 v4, 0, v2
	s_nop 0
	v_add_u32_e32 v3, s2, v1
	v_cvt_f32_u32_e32 v1, v2
	v_rcp_iflag_f32_e32 v1, v1
	s_nop 0
	v_mul_f32_e32 v1, 0x4f7ffffe, v1
	v_cvt_u32_f32_e32 v1, v1
	v_mul_lo_u32 v4, v4, v1
	v_mul_hi_u32 v4, v1, v4
	v_add_u32_e32 v1, v1, v4
	v_mul_hi_u32 v1, v3, v1
	v_mul_lo_u32 v4, v1, v2
	v_sub_u32_e32 v4, v3, v4
	v_cmp_ge_u32_e32 vcc, v4, v2
	v_add_u32_e32 v5, 1, v1
	s_nop 0
	v_cndmask_b32_e32 v1, v1, v5, vcc
	v_sub_u32_e32 v5, v4, v2
	v_cndmask_b32_e32 v4, v4, v5, vcc
	v_cmp_ge_u32_e32 vcc, v4, v2
	v_add_u32_e32 v4, 1, v1
	s_nop 0
	v_cndmask_b32_e32 v1, v1, v4, vcc
	v_add_u32_e32 v4, 1, v3
	v_mad_u64_u32 v[2:3], s[10:11], v2, v1, v[2:3]
	v_cmp_ne_u32_e32 vcc, v4, v2
	s_and_saveexec_b64 s[10:11], vcc
	s_xor_b64 s[10:11], exec, s[10:11]
	s_cbranch_execz .LBB0_1511
	buffer_inv sc1
	v_mov_b32_e32 v0, 0x2000
	global_load_dword v0, v0, s[8:9] offset:1024 sc1
	s_add_u32 s12, s8, 0x2400
	s_addc_u32 s13, s9, 0
	s_waitcnt vmcnt(0)
	v_cmp_eq_u32_e32 vcc, v0, v1
	s_and_saveexec_b64 s[14:15], vcc
	s_cbranch_execz .LBB0_1510
	s_mov_b64 s[16:17], 0

.LBB0_1510:
	s_or_b64 exec, exec, s[14:15]
	s_waitcnt lgkmcnt(0)
	s_waitcnt vmcnt(0)

.LBB0_1514:
	s_or_b64 exec, exec, s[12:13]
	buffer_inv sc1
	s_waitcnt vmcnt(0)
	v_readfirstlane_b32 s2, v2
	v_sub_u32_e32 v3, 0, v0
	s_nop 0
	v_add_u32_e32 v2, s2, v1
	v_cvt_f32_u32_e32 v1, v0
	v_rcp_iflag_f32_e32 v1, v1
	s_nop 0
	v_mul_f32_e32 v1, 0x4f7ffffe, v1
	v_cvt_u32_f32_e32 v1, v1
	v_mul_lo_u32 v3, v3, v1
	v_mul_hi_u32 v3, v1, v3
	v_add_u32_e32 v1, v1, v3
	v_mul_hi_u32 v1, v2, v1
	v_mul_lo_u32 v3, v1, v0
	v_sub_u32_e32 v3, v2, v3
	v_cmp_ge_u32_e32 vcc, v3, v0
	v_add_u32_e32 v4, 1, v1
	s_nop 0
	v_cndmask_b32_e32 v1, v1, v4, vcc
	v_sub_u32_e32 v4, v3, v0
	v_cndmask_b32_e32 v3, v3, v4, vcc
	v_cmp_ge_u32_e32 vcc, v3, v0
	v_add_u32_e32 v3, 1, v1
	v_add_u32_e32 v4, 1, v2
	v_cndmask_b32_e32 v1, v1, v3, vcc
	v_mad_u64_u32 v[2:3], s[10:11], v0, v1, v[0:1]
	v_cmp_ne_u32_e32 vcc, v4, v2
	s_and_saveexec_b64 s[10:11], vcc
	s_xor_b64 s[10:11], exec, s[10:11]
	s_cbranch_execz .LBB0_1519
	global_load_dword v0, v153, s[76:77] sc1
	s_waitcnt vmcnt(0)
	v_cmp_eq_u32_e32 vcc, v0, v1
	s_and_saveexec_b64 s[12:13], vcc
	s_cbranch_execz .LBB0_1518
	s_mov_b64 s[14:15], 0

.LBB0_1525:
	s_or_b64 exec, exec, s[12:13]
.LBB0_1526:
	s_or_b64 exec, exec, s[4:5]
	v_readlane_b32 s2, v253, 48
	s_add_i32 s2, s2, 1
	s_waitcnt lgkmcnt(0)
	v_writelane_b32 v253, s2, 48
	s_barrier
	s_branch .LBB0_1677
